# speedup vs baseline: 1.0062x; 1.0051x over previous
.LBB0_1372:
	s_add_i32 s40, s84, -2
	s_max_i32 s40, s40, 0
	s_lshl_b32 s12, s40, 13
	s_mov_b32 s13, 0
	s_lshl_b32 s24, s83, 13
	s_add_i32 m0, s74, s24
	v_lshl_add_u64 v[80:81], v[134:135], 0, s[12:13]
	global_load_lds_dwordx4 v[80:81], off
	s_lshl_b32 s12, s40, 14
	s_lshl_b32 s24, s83, 14
	s_add_i32 s24, s74, s24
	s_add_i32 m0, s24, 0x6000
	v_lshl_add_u64 v[80:81], v[132:133], 0, s[12:13]
	global_load_lds_dwordx4 v[80:81], off
	s_add_i32 m0, s24, 0x8000
	v_lshl_add_u64 v[80:81], v[80:81], 0, s[26:27]
	global_load_lds_dwordx4 v[80:81], off
	v_lshl_add_u32 v126, s81, 13, v153
	s_lshl_b32 s12, s81, 8
	v_add_u32_e32 v115, v126, v152
	v_add_u32_e32 v114, s12, v154
	v_add_u32_e32 v246, s12, v160
	ds_read_b32 v247, v246
	ds_read_b128 v[208:211], v115 offset:4096
	ds_read_b128 v[224:227], v115
	v_med3_i32 v118, v113, 0, v137
	v_lshlrev_b32_e32 v119, 2, v118
	global_load_dword v164, v119, s[54:55]
	v_add_u32_e32 v116, v126, v155
	v_add_u32_e32 v117, v126, v156
	v_add_u32_e32 v118, v126, v157
	s_waitcnt lgkmcnt(1)
	v_mfma_f32_32x32x16_bf16 v[80:95], v[208:211], v[108:111], 0
	ds_read_b128 v[212:215], v116 offset:4096
	ds_read_b128 v[228:231], v116
	s_waitcnt lgkmcnt(2)
	v_mfma_f32_32x32x16_bf16 v[192:207], v[224:227], v[108:111], 0
	v_max_f32_dpp v248, v247, v247 quad_perm:[1,0,3,2] row_mask:0xf bank_mask:0xf
	ds_read_b128 v[216:219], v117 offset:4096
	ds_read_b128 v[232:235], v117
	s_waitcnt lgkmcnt(3)
	v_mfma_f32_32x32x16_bf16 v[80:95], v[212:215], v[104:107], v[80:95]
	s_nop 1
	v_max_f32_dpp v248, v248, v248 quad_perm:[2,3,0,1] row_mask:0xf bank_mask:0xf
	s_waitcnt lgkmcnt(2)
	v_mfma_f32_32x32x16_bf16 v[192:207], v[228:231], v[104:107], v[192:207]
	s_nop 1
	v_max_f32_dpp v248, v248, v248 row_half_mirror row_mask:0xf bank_mask:0xf
	ds_read_b128 v[220:223], v118 offset:4096
	ds_read_b128 v[236:239], v118
	s_waitcnt lgkmcnt(3)
	v_mfma_f32_32x32x16_bf16 v[80:95], v[216:219], v[100:103], v[80:95]
	s_nop 1
	v_max_f32_dpp v248, v248, v248 row_mirror row_mask:0xf bank_mask:0xf
	s_waitcnt lgkmcnt(2)
	v_mfma_f32_32x32x16_bf16 v[192:207], v[232:235], v[100:103], v[192:207]
	s_nop 1
	v_max_f32_dpp v248, v248, v248 row_bcast:15 row_mask:0xa bank_mask:0xf
	s_waitcnt lgkmcnt(1)
	v_mfma_f32_32x32x16_bf16 v[80:95], v[220:223], v[96:99], v[80:95]
	s_nop 1
	v_max_f32_dpp v248, v248, v248 row_bcast:31 row_mask:0xc bank_mask:0xf
	s_waitcnt lgkmcnt(0)
	v_mfma_f32_32x32x16_bf16 v[192:207], v[236:239], v[96:99], v[192:207]
	s_and_b64 vcc, exec, s[8:9]
	s_cbranch_vccnz .LBB0_1375
	v_sub_u32_e32 v242, v148, v131
	v_cvt_f32_i32_e32 v242, v242
	v_lshl_add_u32 v243, s80, 8, v160
	v_mul_f32_e32 v242, v139, v242
	ds_write_b32 v243, v242
.LBB0_1375:
	s_add_i32 s24, s84, -1
	s_mov_b32 s12, s80
	v_readlane_b32 s93, v248, 63
	s_nop 5
	v_max_f32_e32 v119, v81, v81
	v_max_f32_e32 v120, v80, v80
	v_max_f32_e32 v119, v120, v119
	v_max3_f32 v119, v119, v82, v83
	v_max_f32_e32 v240, v193, v193
	v_max_f32_e32 v241, v192, v192
	v_max3_f32 v119, v119, v84, v85
	v_max_f32_e32 v240, v241, v240
	v_max3_f32 v119, v119, v86, v87
	v_max3_f32 v240, v240, v194, v195
	v_max3_f32 v119, v119, v88, v89
	v_max3_f32 v240, v240, v196, v197
	v_max3_f32 v119, v119, v90, v91
	v_max3_f32 v240, v240, v198, v199
	v_max3_f32 v119, v119, v92, v93
	v_max3_f32 v240, v240, v200, v201
	v_max3_f32 v119, v119, v94, v95
	v_max3_f32 v240, v240, v202, v203
	v_max3_f32 v240, v240, v204, v205
	v_max3_f32 v240, v240, v206, v207
	v_add_f32_e32 v249, s93, v119
	v_cmp_lt_f32_e32 vcc, v249, v112
	s_cmp_eq_u64 vcc, exec
	s_cbranch_scc0 .LBB0_1377
	s_cmp_lt_i32 s84, 2
	s_waitcnt vmcnt(4) lgkmcnt(0)
	s_barrier
	v_subrev_u32_e32 v113, 64, v113
	s_mov_b64 s[42:43], 0
	s_mov_b64 s[40:41], s[10:11]
	s_waitcnt vmcnt(0)
	v_mov_b32_e32 v148, v164
	s_mov_b32 s80, s83
	s_mov_b32 s83, s81
	s_mov_b32 s84, 0
	s_cselect_b64 s[44:45], -1, 0
	s_mov_b32 s81, s12
	s_and_b64 vcc, exec, s[44:45]
	s_cbranch_vccz .LBB0_1378
	ds_read_b128 v[208:211], v114
	ds_read_b128 v[212:215], v114 offset:16
	ds_read_b128 v[216:219], v114 offset:64
	ds_read_b128 v[220:223], v114 offset:80
	s_waitcnt lgkmcnt(0)
	v_pk_add_f32 v[192:193], v[192:193], v[208:209]
	v_pk_add_f32 v[194:195], v[194:195], v[210:211]
	v_pk_add_f32 v[196:197], v[196:197], v[212:213]
	v_pk_add_f32 v[198:199], v[198:199], v[214:215]
	v_pk_add_f32 v[200:201], v[200:201], v[216:217]
	v_pk_add_f32 v[202:203], v[202:203], v[218:219]
	v_pk_add_f32 v[204:205], v[204:205], v[220:221]
	v_pk_add_f32 v[206:207], v[206:207], v[222:223]
	v_max_f32_e32 v240, v193, v193
	v_max_f32_e32 v241, v192, v192
	s_nop 0
	v_max_f32_e32 v240, v241, v240
	v_max3_f32 v240, v240, v194, v195
	v_max3_f32 v240, v240, v196, v197
	v_max3_f32 v240, v240, v198, v199
	v_max3_f32 v240, v240, v200, v201
	v_max3_f32 v240, v240, v202, v203
	v_max3_f32 v240, v240, v204, v205
	v_max3_f32 v240, v240, v206, v207
	v_mov_b32_e32 v241, v240
	s_nop 1
	v_permlane32_swap_b32_e32 v240, v241
	v_max_f32_e32 v241, v241, v241
	v_max_f32_e32 v240, v240, v240
	v_max_f32_e32 v166, v240, v241
	v_mov_b64_e32 v[64:65], v[192:193]
	v_mov_b64_e32 v[66:67], v[194:195]
	v_mov_b64_e32 v[68:69], v[196:197]
	v_mov_b64_e32 v[70:71], v[198:199]
	v_mov_b64_e32 v[72:73], v[200:201]
	v_mov_b64_e32 v[74:75], v[202:203]
	v_mov_b64_e32 v[76:77], v[204:205]
	v_mov_b64_e32 v[78:79], v[206:207]
	s_branch .LBB0_1330

.LBB0_1378:
	s_mov_b32 s84, s24
	v_add_f32_e32 v249, s93, v240
	v_cmp_lt_f32_e32 vcc, v249, v112
	s_cmp_lg_u64 vcc, exec
	s_cbranch_scc1 .Lz_fix2
	s_branch .LBB0_1372
.Lz_fix2:
	ds_read_b128 v[208:211], v114
	ds_read_b128 v[212:215], v114 offset:16
	ds_read_b128 v[216:219], v114 offset:64
	ds_read_b128 v[220:223], v114 offset:80
	s_waitcnt lgkmcnt(0)
	v_pk_add_f32 v[192:193], v[192:193], v[208:209]
	v_pk_add_f32 v[194:195], v[194:195], v[210:211]
	v_pk_add_f32 v[196:197], v[196:197], v[212:213]
	v_pk_add_f32 v[198:199], v[198:199], v[214:215]
	v_pk_add_f32 v[200:201], v[200:201], v[216:217]
	v_pk_add_f32 v[202:203], v[202:203], v[218:219]
	v_pk_add_f32 v[204:205], v[204:205], v[220:221]
	v_pk_add_f32 v[206:207], v[206:207], v[222:223]
	v_max_f32_e32 v240, v193, v193
	v_max_f32_e32 v241, v192, v192
	s_nop 0
	v_max_f32_e32 v240, v241, v240
	v_max3_f32 v240, v240, v194, v195
	v_max3_f32 v240, v240, v196, v197
	v_max3_f32 v240, v240, v198, v199
	v_max3_f32 v240, v240, v200, v201
	v_max3_f32 v240, v240, v202, v203
	v_max3_f32 v240, v240, v204, v205
	v_max3_f32 v240, v240, v206, v207
	v_mov_b32_e32 v241, v240
	s_nop 1
	v_permlane32_swap_b32_e32 v240, v241
	v_max_f32_e32 v241, v241, v241
	v_max_f32_e32 v240, v240, v240
	v_max_f32_e32 v166, v240, v241
	v_mov_b64_e32 v[64:65], v[192:193]
	v_mov_b64_e32 v[66:67], v[194:195]
	v_mov_b64_e32 v[68:69], v[196:197]
	v_mov_b64_e32 v[70:71], v[198:199]
	v_mov_b64_e32 v[72:73], v[200:201]
	v_mov_b64_e32 v[74:75], v[202:203]
	v_mov_b64_e32 v[76:77], v[204:205]
	v_mov_b64_e32 v[78:79], v[206:207]
	s_branch .LBB0_1376
